# v28 + MLA/forgetting-attention LDS-DMA issue moved from loop top into the P*V MFMA groups
# speedup vs baseline: 1.0300x; 1.0068x over previous
; #define LAS __attribute__((address_space(3)))
; __device__ __forceinline__ float max3_(float a, float b, float c) { float r; asm("v_max3_f32 %0, %1, %2, %3" : "=v"(r) : "v"(a), "v"(b), "v"(c)); return r; }
; __device__ __forceinline__ f32x2 pk_sub(f32x2 a, f32x2 b) { f32x2 r; asm("v_pk_add_f32 %0, %1, %2 neg_lo:[0,1] neg_hi:[0,1]" : "=v"(r) : "v"(a), "v"(b)); return r; }
; __device__ __forceinline__ float swap_max(float x) { auto rr = __builtin_amdgcn_permlane32_swap(__float_as_uint(x), __float_as_uint(x), false, false); return fmaxf(__uint_as_float(rr[0]), __uint_as_float(rr[1])); }
; #define AT_BAR() do { asm volatile("" ::: "memory"); __builtin_amdgcn_s_barrier(); asm volatile("" ::: "memory"); } while (0)
; template <int TYPE  >
; __device__ __forceinline__ void attn_item(const Params& P, const int b, const int h, const int qt, LAS unsigned char* lds) {
;     ...
;     for (int it = 0; it < NT; ++it) {
;         const int kt = AT_TILE(it);
;         if (it + 1 < NT) at_waitv<NI>(); else at_waitv<0>();
;         AT_BAR();
;         if (TYPE == 2 && it > 0) { const LAS int* fl = (const LAS int*)(lds + FLAGS + ((it - 1) & 1) * 32);
;             if (fl[0] & fl[1] & fl[2] & fl[3] & fl[4] & fl[5] & fl[6] & fl[7]) break; }
;         if (it + 2 < NT) AT_ISSUE(AT_TILE(it + 2), so2);
;     ...
;                 float mx = m_run;
; #pragma unroll
;                 for (int i = 0; i < 16; ++i) mx = max3_(mx, s0[i], s1[i]);
;                 asm volatile("s_nop 1" : "+v"(mx));
;                 const float mnew = swap_max(mx);
;                 const f32x2 mm = {mnew, mnew}; f32x2 rs2 = {0.f, 0.f};
; #pragma unroll
;                 for (int j = 0; j < 8; ++j) { const f32x2 x0 = pk_sub((f32x2){s0[2 * j], s0[2 * j + 1]}, mm), x1 = pk_sub((f32x2){s1[2 * j], s1[2 * j + 1]}, mm);
.LBB0_1128:
	s_waitcnt vmcnt(5)
	s_add_i32 s12, s10, 0
	s_barrier
	s_cmp_gt_i32 s11, s3
	s_cbranch_scc1 .LBB0_1132
	v_add_u32_e32 v0, s2, v230
	v_add_u32_e32 v214, 0, v0
	v_xad_u32 v215, v0, 32, 0
	v_xad_u32 v231, v0, 64, 0
	v_xor_b32_e32 v0, 0x60, v0
	v_add_u32_e32 v0, 0, v0
	ds_read_b128 v[146:149], v231
	ds_read_b128 v[150:153], v231 offset:12288
	ds_read_b128 v[154:157], v0
	ds_read_b128 v[158:161], v0 offset:12288
	ds_read_b128 v[66:69], v214
	ds_read_b128 v[192:195], v214 offset:128
	ds_read_b128 v[70:73], v214 offset:12288
	ds_read_b128 v[196:199], v214 offset:12416
	ds_read_b128 v[200:203], v215
	ds_read_b128 v[204:207], v215 offset:128
	ds_read_b128 v[236:239], v215 offset:12288
	ds_read_b128 v[240:243], v215 offset:12416
	s_setprio 1
	s_waitcnt lgkmcnt(0)
	v_mfma_f32_32x32x16_bf16 v[82:97], v[66:69], v[142:145], 0
	v_mfma_f32_32x32x16_bf16 v[66:81], v[70:73], v[142:145], 0
	v_mfma_f32_32x32x16_bf16 v[82:97], v[200:203], v[138:141], v[82:97]
	v_mfma_f32_32x32x16_bf16 v[66:81], v[236:239], v[138:141], v[66:81]
	v_mfma_f32_32x32x16_bf16 v[82:97], v[146:149], v[134:137], v[82:97]
	v_mfma_f32_32x32x16_bf16 v[66:81], v[150:153], v[134:137], v[66:81]
	s_setprio 0
	ds_read_b128 v[146:149], v231 offset:128
	ds_read_b128 v[150:153], v231 offset:12416
	ds_read_b128 v[200:203], v0 offset:128
	ds_read_b128 v[236:239], v0 offset:12416
	ds_read_b128 v[244:247], v214 offset:256
	ds_read_b128 v[248:251], v214 offset:12544
	s_setprio 1
	v_mfma_f32_32x32x16_bf16 v[82:97], v[154:157], v[130:133], v[82:97]
	v_mfma_f32_32x32x16_bf16 v[66:81], v[158:161], v[130:133], v[66:81]
	v_mfma_f32_32x32x16_bf16 v[82:97], v[192:195], v[126:129], v[82:97]
	v_mfma_f32_32x32x16_bf16 v[66:81], v[196:199], v[126:129], v[66:81]
	v_mfma_f32_32x32x16_bf16 v[82:97], v[204:207], v[122:125], v[82:97]
	v_mfma_f32_32x32x16_bf16 v[66:81], v[240:243], v[122:125], v[66:81]
	s_setprio 0
	ds_read_b128 v[154:157], v215 offset:256
	ds_read_b128 v[158:161], v215 offset:12544
	ds_read_b128 v[192:195], v231 offset:256
	ds_read_b128 v[196:199], v231 offset:12544
	ds_read_b128 v[204:207], v0 offset:256
	ds_read_b128 v[240:243], v0 offset:12544
	s_setprio 1
	s_waitcnt lgkmcnt(0)
	v_mfma_f32_32x32x16_bf16 v[82:97], v[146:149], v[114:117], v[82:97]
	v_mfma_f32_32x32x16_bf16 v[66:81], v[150:153], v[114:117], v[66:81]
	v_mfma_f32_32x32x16_bf16 v[82:97], v[200:203], v[110:113], v[82:97]
	v_mfma_f32_32x32x16_bf16 v[66:81], v[236:239], v[110:113], v[66:81]
	v_mfma_f32_32x32x16_bf16 v[82:97], v[244:247], v[118:121], v[82:97]
	v_mfma_f32_32x32x16_bf16 v[66:81], v[248:251], v[118:121], v[66:81]
	s_setprio 0
	s_setprio 1
	v_mfma_f32_32x32x16_bf16 v[82:97], v[154:157], v[106:109], v[82:97]
	v_mfma_f32_32x32x16_bf16 v[66:81], v[158:161], v[106:109], v[66:81]
	v_mfma_f32_32x32x16_bf16 v[82:97], v[192:195], v[102:105], v[82:97]
	v_mfma_f32_32x32x16_bf16 v[66:81], v[196:199], v[102:105], v[66:81]
	v_mfma_f32_32x32x16_bf16 v[82:97], v[204:207], v[98:101], v[82:97]
	v_mfma_f32_32x32x16_bf16 v[66:81], v[240:243], v[98:101], v[66:81]
	s_setprio 0
	v_add_u32_e32 v154, s2, v229
	v_add_u32_e32 v0, s2, v228
	v_xor_b32_e32 v155, 64, v154
	v_add_u32_e32 v0, 0, v0
	v_xor_b32_e32 v146, 32, v154
	v_add_u32_e32 v232, 0, v155
	v_xor_b32_e32 v154, 0x60, v154
	s_nop 7
	s_nop 7
	s_nop 3
	v_add_u32_e32 v231, 0, v146
	ds_read_b128 v[150:153], v0 offset:24576
	ds_read_b128 v[146:149], v231
	v_add_u32_e32 v233, 0, v154
	ds_read_b128 v[158:161], v232
	ds_read_b128 v[154:157], v233
	v_max3_f32 v192, v234, v82, v66
	s_nop 0
	v_max3_f32 v192, v192, v83, v67
	s_nop 0
	v_max3_f32 v192, v192, v84, v68
	s_nop 0
	v_max3_f32 v192, v192, v85, v69
	s_nop 0
	v_max3_f32 v192, v192, v86, v70
	s_nop 0
	v_max3_f32 v192, v192, v87, v71
	s_nop 0
	v_max3_f32 v192, v192, v88, v72
	s_nop 0
	v_max3_f32 v192, v192, v89, v73
	s_nop 0
	v_max3_f32 v192, v192, v90, v74
	s_nop 0
	v_max3_f32 v192, v192, v91, v75
	s_nop 0
	v_max3_f32 v192, v192, v92, v76
	s_nop 0
	v_max3_f32 v192, v192, v93, v77
	s_nop 0
	v_max3_f32 v192, v192, v94, v78
	s_nop 0
	v_max3_f32 v192, v192, v95, v79
	s_nop 0
	v_max3_f32 v192, v192, v96, v80
	s_nop 0
	v_max3_f32 v192, v192, v97, v81
	s_nop 0
	s_nop 1
	s_nop 0
	v_mov_b32_e32 v193, v192
	s_nop 1
	v_permlane32_swap_b32_e32 v192, v193
	v_max_f32_e32 v193, v193, v193
	v_max_f32_e32 v192, v192, v192
	v_max_f32_e32 v192, v192, v193
	v_cmp_gt_f32_e32 vcc, v192, v234
	v_mov_b32_e32 v193, v192
	v_pk_add_f32 v[206:207], v[82:83], v[192:193] neg_lo:[0,1] neg_hi:[0,1]
	v_pk_add_f32 v[204:205], v[66:67], v[192:193] neg_lo:[0,1] neg_hi:[0,1]
	v_pk_add_f32 v[202:203], v[84:85], v[192:193] neg_lo:[0,1] neg_hi:[0,1]
	v_pk_add_f32 v[200:201], v[68:69], v[192:193] neg_lo:[0,1] neg_hi:[0,1]
	v_pk_add_f32 v[198:199], v[86:87], v[192:193] neg_lo:[0,1] neg_hi:[0,1]
	v_pk_add_f32 v[196:197], v[70:71], v[192:193] neg_lo:[0,1] neg_hi:[0,1]
	v_pk_add_f32 v[194:195], v[88:89], v[192:193] neg_lo:[0,1] neg_hi:[0,1]
	v_pk_add_f32 v[88:89], v[72:73], v[192:193] neg_lo:[0,1] neg_hi:[0,1]
	v_pk_add_f32 v[86:87], v[90:91], v[192:193] neg_lo:[0,1] neg_hi:[0,1]
	v_pk_add_f32 v[84:85], v[74:75], v[192:193] neg_lo:[0,1] neg_hi:[0,1]
	v_pk_add_f32 v[82:83], v[92:93], v[192:193] neg_lo:[0,1] neg_hi:[0,1]
	v_pk_add_f32 v[74:75], v[76:77], v[192:193] neg_lo:[0,1] neg_hi:[0,1]
	v_pk_add_f32 v[72:73], v[94:95], v[192:193] neg_lo:[0,1] neg_hi:[0,1]
	v_pk_add_f32 v[70:71], v[78:79], v[192:193] neg_lo:[0,1] neg_hi:[0,1]
	v_pk_add_f32 v[68:69], v[96:97], v[192:193] neg_lo:[0,1] neg_hi:[0,1]
	v_pk_add_f32 v[66:67], v[80:81], v[192:193] neg_lo:[0,1] neg_hi:[0,1]
	s_cbranch_vccz .LBB0_1131
; __device__ __forceinline__ float exp2_(float x) { return __builtin_amdgcn_exp2f(x); }
; #define AT_RV(vf, mb) do { vf[0] = *(const LAS bf16x8*)(lds + vb + (mb) * 4096); vf[1] = *(const LAS bf16x8*)(lds + (vb ^ 32u) + (mb) * 4096); \
;                 vf[2] = *(const LAS bf16x8*)(lds + (vb ^ 64u) + (mb) * 4096); vf[3] = *(const LAS bf16x8*)(lds + (vb ^ 96u) + (mb) * 4096); } while (0)
; #define AT_PV(o, vf) do { __builtin_amdgcn_s_setprio(1); o = MFMA32(vf[0], p00, o); o = MFMA32(vf[1], p01, o); o = MFMA32(vf[2], p10, o); o = MFMA32(vf[3], p11, o); __builtin_amdgcn_s_setprio(0); } while (0)
; template <int TYPE  >
; __device__ __forceinline__ void attn_item(const Params& P, const int b, const int h, const int qt, LAS unsigned char* lds) {
;     ...
;                     s0[2 * j] = exp2_(x0[0]); s0[2 * j + 1] = exp2_(x0[1]); s1[2 * j] = exp2_(x1[0]); s1[2 * j + 1] = exp2_(x1[1]);
;                     rs2 += (f32x2){s0[2 * j], s0[2 * j + 1]} + (f32x2){s1[2 * j], s1[2 * j + 1]}; }
;                 const float rs = rs2[0] + rs2[1];
;                 if (__any(mnew > m_run)) {
;                     const float alpha = exp2_(m_run - mnew);
;                     l_run *= alpha; o0 *= alpha; o1 *= alpha; o2 *= alpha; o3 *= alpha;
;                 }
;                 l_run += rs; m_run = mnew;
;             }
;             const bf16x8 p00 = pack8(s0, 0), p01 = pack8(s0, 1), p10 = pack8(s1, 0), p11 = pack8(s1, 1);
;     ...
;             __builtin_amdgcn_sched_barrier(0);
;             AT_RV(vf1, 1); AT_PV(o0, vf0); __builtin_amdgcn_sched_barrier(0);
;             AT_RV(vf2, 2); AT_PV(o1, vf1); __builtin_amdgcn_sched_barrier(0);
;             AT_RV(vf3, 3); AT_PV(o2, vf2); __builtin_amdgcn_sched_barrier(0);
;             AT_PV(o3, vf3); __builtin_amdgcn_sched_barrier(0);
	v_sub_f32_e32 v76, v234, v192
	v_exp_f32_e32 v76, v76
	s_nop 0
	v_mul_f32_e32 v227, v227, v76
	v_pk_mul_f32 v[64:65], v[64:65], v[76:77] op_sel_hi:[1,0]
	v_pk_mul_f32 v[62:63], v[62:63], v[76:77] op_sel_hi:[1,0]
	v_pk_mul_f32 v[60:61], v[60:61], v[76:77] op_sel_hi:[1,0]
	v_pk_mul_f32 v[58:59], v[58:59], v[76:77] op_sel_hi:[1,0]
	v_pk_mul_f32 v[56:57], v[56:57], v[76:77] op_sel_hi:[1,0]
	v_pk_mul_f32 v[54:55], v[54:55], v[76:77] op_sel_hi:[1,0]
	v_pk_mul_f32 v[52:53], v[52:53], v[76:77] op_sel_hi:[1,0]
	v_pk_mul_f32 v[50:51], v[50:51], v[76:77] op_sel_hi:[1,0]
	v_pk_mul_f32 v[48:49], v[48:49], v[76:77] op_sel_hi:[1,0]
	v_pk_mul_f32 v[46:47], v[46:47], v[76:77] op_sel_hi:[1,0]
	v_pk_mul_f32 v[44:45], v[44:45], v[76:77] op_sel_hi:[1,0]
	v_pk_mul_f32 v[42:43], v[42:43], v[76:77] op_sel_hi:[1,0]
	v_pk_mul_f32 v[40:41], v[40:41], v[76:77] op_sel_hi:[1,0]
	v_pk_mul_f32 v[38:39], v[38:39], v[76:77] op_sel_hi:[1,0]
	v_pk_mul_f32 v[36:37], v[36:37], v[76:77] op_sel_hi:[1,0]
	v_pk_mul_f32 v[34:35], v[34:35], v[76:77] op_sel_hi:[1,0]
	v_pk_mul_f32 v[32:33], v[32:33], v[76:77] op_sel_hi:[1,0]
	v_pk_mul_f32 v[30:31], v[30:31], v[76:77] op_sel_hi:[1,0]
	v_pk_mul_f32 v[28:29], v[28:29], v[76:77] op_sel_hi:[1,0]
	v_pk_mul_f32 v[26:27], v[26:27], v[76:77] op_sel_hi:[1,0]
	v_pk_mul_f32 v[24:25], v[24:25], v[76:77] op_sel_hi:[1,0]
	v_pk_mul_f32 v[22:23], v[22:23], v[76:77] op_sel_hi:[1,0]
	v_pk_mul_f32 v[20:21], v[20:21], v[76:77] op_sel_hi:[1,0]
	v_pk_mul_f32 v[18:19], v[18:19], v[76:77] op_sel_hi:[1,0]
	v_pk_mul_f32 v[16:17], v[16:17], v[76:77] op_sel_hi:[1,0]
	v_pk_mul_f32 v[14:15], v[14:15], v[76:77] op_sel_hi:[1,0]
	v_pk_mul_f32 v[12:13], v[12:13], v[76:77] op_sel_hi:[1,0]
	v_pk_mul_f32 v[10:11], v[10:11], v[76:77] op_sel_hi:[1,0]
	v_pk_mul_f32 v[8:9], v[8:9], v[76:77] op_sel_hi:[1,0]
	v_pk_mul_f32 v[6:7], v[6:7], v[76:77] op_sel_hi:[1,0]
	v_pk_mul_f32 v[4:5], v[4:5], v[76:77] op_sel_hi:[1,0]
	v_pk_mul_f32 v[2:3], v[2:3], v[76:77] op_sel_hi:[1,0]
.LBB0_1131:
	v_exp_f32_e32 v76, v206
	v_exp_f32_e32 v77, v207
	v_exp_f32_e32 v78, v204
	v_exp_f32_e32 v79, v205
	v_exp_f32_e32 v80, v202
	v_exp_f32_e32 v81, v203
	v_exp_f32_e32 v90, v200
	v_exp_f32_e32 v91, v201
	v_exp_f32_e32 v96, v198
	v_exp_f32_e32 v97, v199
	v_exp_f32_e32 v196, v196
	v_exp_f32_e32 v197, v197
	v_exp_f32_e32 v194, v194
	v_exp_f32_e32 v195, v195
	v_exp_f32_e32 v88, v88
	v_exp_f32_e32 v89, v89
	v_pk_add_f32 v[92:93], v[76:77], v[78:79]
	v_pk_add_f32 v[94:95], v[80:81], v[90:91]
	v_pk_add_f32 v[92:93], v[92:93], 0 op_sel_hi:[1,0]
	v_exp_f32_e32 v86, v86
	v_pk_add_f32 v[92:93], v[92:93], v[94:95]
	v_pk_add_f32 v[94:95], v[96:97], v[196:197]
	v_exp_f32_e32 v87, v87
	v_exp_f32_e32 v84, v84
	v_exp_f32_e32 v85, v85
	v_pk_add_f32 v[92:93], v[92:93], v[94:95]
	v_pk_add_f32 v[94:95], v[194:195], v[88:89]
	v_exp_f32_e32 v82, v82
	v_exp_f32_e32 v83, v83
	v_exp_f32_e32 v198, v74
	v_exp_f32_e32 v199, v75
	v_pk_add_f32 v[74:75], v[92:93], v[94:95]
	v_exp_f32_e32 v72, v72
	v_exp_f32_e32 v73, v73
	v_exp_f32_e32 v94, v70
	v_exp_f32_e32 v95, v71
	v_exp_f32_e32 v200, v68
	v_exp_f32_e32 v201, v69
	v_exp_f32_e32 v202, v66
	v_exp_f32_e32 v203, v67
	v_pk_add_f32 v[92:93], v[86:87], v[84:85]
	v_pk_add_f32 v[68:69], v[72:73], v[94:95]
	v_pk_add_f32 v[74:75], v[74:75], v[92:93]
	v_pk_add_f32 v[92:93], v[82:83], v[198:199]
	v_cvt_pk_bf16_f32 v70, v86, v87
	v_pk_add_f32 v[66:67], v[74:75], v[92:93]
	v_cvt_pk_bf16_f32 v71, v82, v83
	v_pk_add_f32 v[66:67], v[66:67], v[68:69]
	v_pk_add_f32 v[68:69], v[200:201], v[202:203]
	v_cvt_pk_bf16_f32 v72, v72, v73
	v_pk_add_f32 v[66:67], v[66:67], v[68:69]
	v_cvt_pk_bf16_f32 v68, v96, v97
	v_add_f32_e32 v66, v66, v67
	v_add_f32_e32 v227, v66, v227
	v_cvt_pk_bf16_f32 v66, v76, v77
	v_cvt_pk_bf16_f32 v67, v80, v81
	v_cvt_pk_bf16_f32 v69, v194, v195
	v_cvt_pk_bf16_f32 v73, v200, v201
	v_cvt_pk_bf16_f32 v74, v78, v79
	v_cvt_pk_bf16_f32 v75, v90, v91
	v_cvt_pk_bf16_f32 v76, v196, v197
	v_cvt_pk_bf16_f32 v77, v88, v89
	v_cvt_pk_bf16_f32 v78, v84, v85
	v_cvt_pk_bf16_f32 v79, v198, v199
	v_cvt_pk_bf16_f32 v80, v94, v95
	v_cvt_pk_bf16_f32 v81, v202, v203
	ds_read_b128 v[82:85], v0 offset:28672
	ds_read_b128 v[86:89], v231 offset:4096
	ds_read_b128 v[90:93], v232 offset:4096
	ds_read_b128 v[94:97], v233 offset:4096
	s_setprio 1
	s_waitcnt lgkmcnt(0)
	v_mfma_f32_32x32x16_bf16 v[50:65], v[150:153], v[66:69], v[50:65]
	v_mfma_f32_32x32x16_bf16 v[50:65], v[146:149], v[70:73], v[50:65]
	v_mfma_f32_32x32x16_bf16 v[50:65], v[158:161], v[74:77], v[50:65]
	v_mfma_f32_32x32x16_bf16 v[50:65], v[154:157], v[78:81], v[50:65]
	s_setprio 0
	s_add_i32 m0, s12, s4
	s_nop 0
	global_load_lds_dwordx4 v[190:191], off
	s_add_i32 m0, s12, s5
	s_nop 0
	global_load_lds_dwordx4 v[188:189], off
	ds_read_b128 v[146:149], v0 offset:32768
	ds_read_b128 v[150:153], v231 offset:8192
	ds_read_b128 v[154:157], v232 offset:8192
	ds_read_b128 v[158:161], v233 offset:8192
	s_setprio 1
	v_mfma_f32_32x32x16_bf16 v[34:49], v[82:85], v[66:69], v[34:49]
	v_mfma_f32_32x32x16_bf16 v[34:49], v[86:89], v[70:73], v[34:49]
	v_mfma_f32_32x32x16_bf16 v[34:49], v[90:93], v[74:77], v[34:49]
	v_mfma_f32_32x32x16_bf16 v[34:49], v[94:97], v[78:81], v[34:49]
	s_setprio 0
	s_add_i32 m0, s12, s7
	s_add_i32 s12, s12, s8
	global_load_lds_dwordx4 v[186:187], off
	s_add_i32 m0, s12, 0x6000
	s_nop 0
	global_load_lds_dwordx4 v[184:185], off
	ds_read_b128 v[82:85], v0 offset:36864
	ds_read_b128 v[86:89], v231 offset:12288
	ds_read_b128 v[90:93], v232 offset:12288
	ds_read_b128 v[94:97], v233 offset:12288
	s_setprio 1
	s_waitcnt lgkmcnt(0)
	v_mfma_f32_32x32x16_bf16 v[18:33], v[146:149], v[66:69], v[18:33]
	v_mfma_f32_32x32x16_bf16 v[18:33], v[150:153], v[70:73], v[18:33]
	v_mfma_f32_32x32x16_bf16 v[18:33], v[154:157], v[74:77], v[18:33]
	v_mfma_f32_32x32x16_bf16 v[18:33], v[158:161], v[78:81], v[18:33]
	s_setprio 0
	s_add_i32 m0, s12, 0x6400
	s_nop 0
	global_load_lds_dwordx4 v[182:183], off
	s_setprio 1
	v_mfma_f32_32x32x16_bf16 v[2:17], v[82:85], v[66:69], v[2:17]
	v_mfma_f32_32x32x16_bf16 v[2:17], v[86:89], v[70:73], v[2:17]
	v_mfma_f32_32x32x16_bf16 v[2:17], v[90:93], v[74:77], v[2:17]
	v_mfma_f32_32x32x16_bf16 v[2:17], v[94:97], v[78:81], v[2:17]
	s_setprio 0
	s_branch .LBB0_1133
.LBB0_1132:
	s_add_i32 m0, s12, s4
	s_nop 0
	global_load_lds_dwordx4 v[190:191], off
	s_add_i32 m0, s12, s5
	s_nop 0
	global_load_lds_dwordx4 v[188:189], off
	s_add_i32 m0, s12, s7
	s_add_i32 s12, s12, s8
	global_load_lds_dwordx4 v[186:187], off
	s_add_i32 m0, s12, 0x6000
	s_nop 0
	global_load_lds_dwordx4 v[184:185], off
	s_add_i32 m0, s12, 0x6400
	s_nop 0
	global_load_lds_dwordx4 v[182:183], off
	v_mov_b32_e32 v192, v234

; #define LAS __attribute__((address_space(3)))
; __device__ __forceinline__ f32x2 pk_sub(f32x2 a, f32x2 b) { f32x2 r; asm("v_pk_add_f32 %0, %1, %2 neg_lo:[0,1] neg_hi:[0,1]" : "=v"(r) : "v"(a), "v"(b)); return r; }
; #define AT_BAR() do { asm volatile("" ::: "memory"); __builtin_amdgcn_s_barrier(); asm volatile("" ::: "memory"); } while (0)
; template <int TYPE  >
; __device__ __forceinline__ void attn_item(const Params& P, const int b, const int h, const int qt, LAS unsigned char* lds) {
;     ...
;     for (int it = 0; it < NT; ++it) {
;         const int kt = AT_TILE(it);
;         if (it + 1 < NT) at_waitv<NI>(); else at_waitv<0>();
;         AT_BAR();
;         if (TYPE == 2 && it > 0) { const LAS int* fl = (const LAS int*)(lds + FLAGS + ((it - 1) & 1) * 32);
;             if (fl[0] & fl[1] & fl[2] & fl[3] & fl[4] & fl[5] & fl[6] & fl[7]) break; }
;         if (it + 2 < NT) AT_ISSUE(AT_TILE(it + 2), so2);
;     ...
;             if (!have_s) { AT_QK(so); }
;             const unsigned vb = a0v + so;
;             bf16x8 vf0[4], vf1[4], vf2[4], vf3[4];
;     ...
;             AT_RV(vf0, 0);
;             __builtin_amdgcn_sched_barrier(0);
;             const bool diag = (kt == wlast);
;             const int key0 = kt * 64 + 8 * hh;
;             if (TYPE == 2) {
;                 if (diag) {
; #pragma unroll
;                     for (int i = 0; i < 16; ++i) { const int key = key0 + 16 * (i >> 3) + (i & 7); if (key >= tq) s0[i] = -1e30f; if (key + 32 >= tq) s1[i] = -1e30f; } }
;                 sb_sub(s1, carry, hh); sb_sub(s0, carry, hh);
;             } else {
;                 if (TYPE == 1) { const LAS float* fb = (const LAS float*)(lds + so + KREG + VREG + wid * 256) + 8 * hh;
; #pragma unroll
;                     for (int j = 0; j < 8; ++j) {
;                         const f32x2 b0 = *(const LAS f32x2*)(fb + 16 * (j >> 2) + 2 * (j & 3)), b1 = *(const LAS f32x2*)(fb + 32 + 16 * (j >> 2) + 2 * (j & 3));
;                         const f32x2 x0 = pk_sub((f32x2){s0[2 * j], s0[2 * j + 1]}, b0), x1 = pk_sub((f32x2){s1[2 * j], s1[2 * j + 1]}, b1);
;                         s0[2 * j] = x0[0]; s0[2 * j + 1] = x0[1]; s1[2 * j] = x1[0]; s1[2 * j + 1] = x1[1]; }
;                     if (diag) {
; #pragma unroll
;                         for (int i = 0; i < 16; ++i) { const int key = key0 + 16 * (i >> 3) + (i & 7); if (key > tq) s0[i] = -1e30f; if (key + 32 > tq) s1[i] = -1e30f; } } }
.LBB0_1151:
	s_barrier
.LBB0_1153:
	s_cmp_gt_i32 s16, s11
	s_cbranch_scc1 .Lfx_skipdma
	v_add_u32_e32 v0, s13, v187
	v_add_u32_e32 v70, 0, v0
	v_xad_u32 v74, v0, 32, 0
	ds_read_b128 v[66:69], v70
	ds_read_b128 v[70:73], v70 offset:8192
	ds_read_b128 v[130:133], v74
	ds_read_b128 v[134:137], v74 offset:8192
	v_xad_u32 v74, v0, 64, 0
	ds_read_b128 v[138:141], v74
	ds_read_b128 v[142:145], v74 offset:8192
	v_xor_b32_e32 v74, 0x60, v0
	v_add_u32_e32 v74, 0, v74
	ds_read_b128 v[156:159], v74
	ds_read_b128 v[176:179], v74 offset:8192
	v_xor_b32_e32 v74, 0x80, v0
	v_add_u32_e32 v74, 0, v74
	ds_read_b128 v[180:183], v74
	ds_read_b128 v[198:201], v74 offset:8192
	v_xor_b32_e32 v74, 0xa0, v0
	v_add_u32_e32 v74, 0, v74
	ds_read_b128 v[202:205], v74
	ds_read_b128 v[226:229], v74 offset:8192
	v_xor_b32_e32 v74, 0xc0, v0
	v_xor_b32_e32 v0, 0xe0, v0
	v_add_u32_e32 v74, 0, v74
	v_add_u32_e32 v0, 0, v0
	ds_read_b128 v[230:233], v74
	ds_read_b128 v[234:237], v74 offset:8192
	ds_read_b128 v[238:241], v0
	ds_read_b128 v[242:245], v0 offset:8192
	s_setprio 1
	s_waitcnt lgkmcnt(0)
	v_mfma_f32_32x32x16_bf16 v[82:97], v[66:69], v[98:101], 0
	v_mfma_f32_32x32x16_bf16 v[66:81], v[70:73], v[98:101], 0
	v_mfma_f32_32x32x16_bf16 v[82:97], v[130:133], v[102:105], v[82:97]
	v_mfma_f32_32x32x16_bf16 v[66:81], v[134:137], v[102:105], v[66:81]
	v_mfma_f32_32x32x16_bf16 v[82:97], v[138:141], v[106:109], v[82:97]
	v_mfma_f32_32x32x16_bf16 v[66:81], v[142:145], v[106:109], v[66:81]
	v_mfma_f32_32x32x16_bf16 v[82:97], v[156:159], v[110:113], v[82:97]
	v_mfma_f32_32x32x16_bf16 v[66:81], v[176:179], v[110:113], v[66:81]
	s_setprio 0
	s_setprio 1
	v_mfma_f32_32x32x16_bf16 v[82:97], v[180:183], v[114:117], v[82:97]
	v_mfma_f32_32x32x16_bf16 v[66:81], v[198:201], v[114:117], v[66:81]
	v_mfma_f32_32x32x16_bf16 v[82:97], v[202:205], v[118:121], v[82:97]
	v_mfma_f32_32x32x16_bf16 v[66:81], v[226:229], v[118:121], v[66:81]
	v_mfma_f32_32x32x16_bf16 v[82:97], v[230:233], v[122:125], v[82:97]
	v_mfma_f32_32x32x16_bf16 v[66:81], v[234:237], v[122:125], v[66:81]
	v_mfma_f32_32x32x16_bf16 v[82:97], v[238:241], v[126:129], v[82:97]
	v_mfma_f32_32x32x16_bf16 v[66:81], v[242:245], v[126:129], v[66:81]
	s_setprio 0
	v_add_u32_e32 v138, s13, v190
	v_add_u32_e32 v0, s13, v189
	v_xor_b32_e32 v139, 64, v138
	v_add_u32_e32 v0, 0, v0
	v_xor_b32_e32 v130, 32, v138
	v_add_u32_e32 v194, 0, v139
	v_xor_b32_e32 v138, 0x60, v138
	s_nop 7
	s_nop 7
	s_nop 3
	v_add_u32_e32 v193, 0, v130
	ds_read_b128 v[134:137], v0 offset:16384
	ds_read_b128 v[130:133], v193
	v_add_u32_e32 v195, 0, v138
	ds_read_b128 v[142:145], v194
	ds_read_b128 v[138:141], v195
	v_add_u32_e32 v156, s13, v191
	v_add_u32_e32 v184, 0x8000, v156
	ds_read2_b64 v[198:201], v184 offset1:1
	ds_read2_b64 v[202:205], v184 offset0:2 offset1:3
	ds_read2_b64 v[226:229], v184 offset0:16 offset1:17
	ds_read2_b64 v[230:233], v184 offset0:18 offset1:19
	ds_read2_b64 v[234:237], v184 offset0:8 offset1:9
	ds_read2_b64 v[238:241], v184 offset0:24 offset1:25
	ds_read2_b64 v[242:245], v184 offset0:10 offset1:11
	ds_read2_b64 v[246:249], v184 offset0:26 offset1:27
	s_cmp_lg_u32 s11, s16
	s_waitcnt lgkmcnt(0)
	v_pk_add_f32 v[82:83], v[82:83], v[198:199] neg_lo:[0,1] neg_hi:[0,1]
	v_pk_add_f32 v[158:159], v[66:67], v[226:227] neg_lo:[0,1] neg_hi:[0,1]
	v_pk_add_f32 v[156:157], v[84:85], v[200:201] neg_lo:[0,1] neg_hi:[0,1]
	v_pk_add_f32 v[84:85], v[68:69], v[228:229] neg_lo:[0,1] neg_hi:[0,1]
	v_pk_add_f32 v[68:69], v[86:87], v[202:203] neg_lo:[0,1] neg_hi:[0,1]
	v_pk_add_f32 v[86:87], v[88:89], v[204:205] neg_lo:[0,1] neg_hi:[0,1]
	v_pk_add_f32 v[160:161], v[70:71], v[230:231] neg_lo:[0,1] neg_hi:[0,1]
	v_pk_add_f32 v[70:71], v[72:73], v[232:233] neg_lo:[0,1] neg_hi:[0,1]
	v_pk_add_f32 v[72:73], v[90:91], v[234:235] neg_lo:[0,1] neg_hi:[0,1]
	v_pk_add_f32 v[88:89], v[92:93], v[236:237] neg_lo:[0,1] neg_hi:[0,1]
	v_pk_add_f32 v[90:91], v[74:75], v[238:239] neg_lo:[0,1] neg_hi:[0,1]
	v_pk_add_f32 v[74:75], v[76:77], v[240:241] neg_lo:[0,1] neg_hi:[0,1]
	v_pk_add_f32 v[76:77], v[94:95], v[242:243] neg_lo:[0,1] neg_hi:[0,1]
	v_pk_add_f32 v[94:95], v[78:79], v[246:247] neg_lo:[0,1] neg_hi:[0,1]
	v_pk_add_f32 v[92:93], v[96:97], v[244:245] neg_lo:[0,1] neg_hi:[0,1]
	v_pk_add_f32 v[78:79], v[80:81], v[248:249] neg_lo:[0,1] neg_hi:[0,1]
	s_cbranch_scc1 .LBB0_1156
	v_cndmask_b32_e64 v66, v82, v223, s[38:39]
	v_cndmask_b32_e64 v158, v158, v223, s[40:41]
	v_cndmask_b32_e64 v82, v66, v82, s[42:43]
	v_cndmask_b32_e64 v83, v223, v83, s[42:43]
	v_cndmask_b32_e64 v159, v159, v223, s[44:45]
	v_cndmask_b32_e64 v156, v156, v223, s[46:47]
	v_cndmask_b32_e64 v84, v84, v223, s[48:49]
	v_cndmask_b32_e64 v157, v157, v223, s[50:51]
	v_cndmask_b32_e64 v85, v85, v223, s[52:53]
	v_cndmask_b32_e64 v68, v68, v223, s[54:55]
	v_cndmask_b32_e64 v160, v160, v223, s[56:57]
	v_cndmask_b32_e64 v69, v69, v223, s[58:59]
	v_cndmask_b32_e64 v161, v161, v223, s[60:61]
	v_cndmask_b32_e64 v86, v86, v223, s[62:63]
	v_cndmask_b32_e64 v70, v70, v223, s[64:65]
	v_cndmask_b32_e64 v87, v87, v223, s[66:67]
	v_cndmask_b32_e64 v71, v71, v223, s[68:69]
	v_cndmask_b32_e64 v72, v72, v223, s[70:71]
	v_cndmask_b32_e64 v90, v90, v223, s[72:73]
	v_cndmask_b32_e64 v73, v73, v223, s[74:75]
	v_cndmask_b32_e64 v91, v91, v223, s[76:77]
	v_cndmask_b32_e64 v88, v88, v223, s[78:79]
	v_cndmask_b32_e64 v74, v74, v223, s[4:5]
	v_cndmask_b32_e64 v89, v89, v223, s[80:81]
	v_cndmask_b32_e64 v75, v75, v223, s[82:83]
	v_cndmask_b32_e64 v76, v76, v223, s[6:7]
	v_cndmask_b32_e64 v94, v94, v223, s[84:85]
	v_cndmask_b32_e64 v77, v77, v223, s[86:87]
	v_cndmask_b32_e64 v95, v95, v223, s[88:89]
	v_cndmask_b32_e64 v92, v92, v223, s[90:91]
	v_cndmask_b32_e64 v78, v78, v223, s[92:93]
	v_cndmask_b32_e64 v93, v93, v223, s[94:95]
	v_cndmask_b32_e64 v79, v79, v223, s[96:97]

; #define AT_RV(vf, mb) do { vf[0] = *(const LAS bf16x8*)(lds + vb + (mb) * 4096); vf[1] = *(const LAS bf16x8*)(lds + (vb ^ 32u) + (mb) * 4096); \
;                 vf[2] = *(const LAS bf16x8*)(lds + (vb ^ 64u) + (mb) * 4096); vf[3] = *(const LAS bf16x8*)(lds + (vb ^ 96u) + (mb) * 4096); } while (0)
; #define AT_PV(o, vf) do { __builtin_amdgcn_s_setprio(1); o = MFMA32(vf[0], p00, o); o = MFMA32(vf[1], p01, o); o = MFMA32(vf[2], p10, o); o = MFMA32(vf[3], p11, o); __builtin_amdgcn_s_setprio(0); } while (0)
; template <int TYPE  >
; __device__ __forceinline__ void attn_item(const Params& P, const int b, const int h, const int qt, LAS unsigned char* lds) {
;     ...
;         if (it + 2 < NT) AT_ISSUE(AT_TILE(it + 2), so2);
;     ...
;             const bf16x8 p00 = pack8(s0, 0), p01 = pack8(s0, 1), p10 = pack8(s1, 0), p11 = pack8(s1, 1);
;     ...
;             __builtin_amdgcn_sched_barrier(0);
;             AT_RV(vf1, 1); AT_PV(o0, vf0); __builtin_amdgcn_sched_barrier(0);
;             AT_RV(vf2, 2); AT_PV(o1, vf1); __builtin_amdgcn_sched_barrier(0);
;             AT_RV(vf3, 3); AT_PV(o2, vf2); __builtin_amdgcn_sched_barrier(0);
;             AT_PV(o3, vf3); __builtin_amdgcn_sched_barrier(0);
.LBB0_1158:
	v_exp_f32_e32 v76, v184
	v_exp_f32_e32 v77, v185
	v_exp_f32_e32 v78, v182
	v_exp_f32_e32 v79, v183
	v_exp_f32_e32 v88, v180
	v_exp_f32_e32 v89, v181
	v_exp_f32_e32 v90, v178
	v_exp_f32_e32 v91, v179
	v_exp_f32_e32 v160, v176
	v_exp_f32_e32 v161, v177
	v_exp_f32_e32 v158, v158
	v_exp_f32_e32 v159, v159
	v_exp_f32_e32 v156, v156
	v_exp_f32_e32 v157, v157
	v_exp_f32_e32 v96, v96
	v_exp_f32_e32 v97, v97
	v_pk_add_f32 v[92:93], v[76:77], v[78:79]
	v_pk_add_f32 v[94:95], v[88:89], v[90:91]
	v_pk_add_f32 v[92:93], v[92:93], 0 op_sel_hi:[1,0]
	v_exp_f32_e32 v86, v86
	v_pk_add_f32 v[92:93], v[92:93], v[94:95]
	v_pk_add_f32 v[94:95], v[160:161], v[158:159]
	v_exp_f32_e32 v87, v87
	v_exp_f32_e32 v84, v84
	v_exp_f32_e32 v85, v85
	v_pk_add_f32 v[92:93], v[92:93], v[94:95]
	v_pk_add_f32 v[94:95], v[156:157], v[96:97]
	v_exp_f32_e32 v82, v82
	v_exp_f32_e32 v83, v83
	v_exp_f32_e32 v176, v80
	v_exp_f32_e32 v177, v81
	v_pk_add_f32 v[80:81], v[92:93], v[94:95]
	v_exp_f32_e32 v74, v74
	v_exp_f32_e32 v75, v75
	v_exp_f32_e32 v94, v72
	v_exp_f32_e32 v95, v73
	v_exp_f32_e32 v178, v70
	v_exp_f32_e32 v179, v71
	v_exp_f32_e32 v180, v68
	v_exp_f32_e32 v181, v69
	v_pk_add_f32 v[92:93], v[86:87], v[84:85]
	v_pk_add_f32 v[70:71], v[74:75], v[94:95]
	v_pk_add_f32 v[80:81], v[80:81], v[92:93]
	v_pk_add_f32 v[92:93], v[82:83], v[176:177]
	v_cvt_pk_bf16_f32 v72, v86, v87
	v_pk_add_f32 v[68:69], v[80:81], v[92:93]
	v_cvt_pk_bf16_f32 v73, v82, v83
	v_pk_add_f32 v[68:69], v[68:69], v[70:71]
	v_pk_add_f32 v[70:71], v[178:179], v[180:181]
	v_cvt_pk_bf16_f32 v74, v74, v75
	v_pk_add_f32 v[68:69], v[68:69], v[70:71]
	v_cvt_pk_bf16_f32 v70, v160, v161
	v_add_f32_e32 v67, v68, v69
	v_add_f32_e32 v192, v67, v192
	v_cvt_pk_bf16_f32 v68, v76, v77
	v_cvt_pk_bf16_f32 v69, v88, v89
	v_cvt_pk_bf16_f32 v71, v156, v157
	v_cvt_pk_bf16_f32 v75, v178, v179
	v_cvt_pk_bf16_f32 v76, v78, v79
	v_cvt_pk_bf16_f32 v77, v90, v91
	v_cvt_pk_bf16_f32 v78, v158, v159
	v_cvt_pk_bf16_f32 v79, v96, v97
	v_cvt_pk_bf16_f32 v80, v84, v85
	v_cvt_pk_bf16_f32 v81, v176, v177
	v_cvt_pk_bf16_f32 v82, v94, v95
	v_cvt_pk_bf16_f32 v83, v180, v181
	ds_read_b128 v[84:87], v0 offset:20480
	ds_read_b128 v[88:91], v193 offset:4096
	ds_read_b128 v[92:95], v194 offset:4096
	ds_read_b128 v[156:159], v195 offset:4096
	s_setprio 1
	v_mfma_f32_32x32x16_bf16 v[50:65], v[134:137], v[68:71], v[50:65]
	v_mfma_f32_32x32x16_bf16 v[50:65], v[130:133], v[72:75], v[50:65]
	v_mfma_f32_32x32x16_bf16 v[50:65], v[142:145], v[76:79], v[50:65]
	v_mfma_f32_32x32x16_bf16 v[50:65], v[138:141], v[80:83], v[50:65]
	s_setprio 0
	s_add_i32 s8, s16, 2
	s_cmp_ge_u32 s8, s36
	s_cbranch_scc1 .Lfx_nodma
	s_add_i32 s8, s3, s14
	v_lshl_add_u64 v[226:227], s[30:31], 0, v[154:155]
	s_mov_b32 m0, s8
	s_nop 0
	global_load_lds_dwordx4 v[226:227], off
	s_add_i32 m0, s8, 0x400
	s_add_i32 s8, s14, 0
	v_lshl_add_u64 v[226:227], s[30:31], 0, v[152:153]
	s_add_i32 s9, s8, s2
	global_load_lds_dwordx4 v[226:227], off
	s_add_i32 m0, s9, 0x4000
	v_lshl_add_u64 v[226:227], s[30:31], 0, v[150:151]
	global_load_lds_dwordx4 v[226:227], off
	v_lshl_add_u64 v[226:227], s[30:31], 0, v[148:149]
	s_add_i32 m0, s9, 0x4400
	s_add_i32 s8, s8, s12
	global_load_lds_dwordx4 v[226:227], off
	v_lshl_add_u64 v[226:227], s[30:31], 0, v[146:147]
	s_add_i32 m0, s8, 0x8000
	s_nop 0
	global_load_lds_dword v[226:227], off
.Lfx_nodma:
	ds_read_b128 v[130:133], v0 offset:24576
	ds_read_b128 v[134:137], v193 offset:8192
	ds_read_b128 v[138:141], v194 offset:8192
	ds_read_b128 v[142:145], v195 offset:8192
	s_setprio 1
	s_waitcnt lgkmcnt(0)
	v_mfma_f32_32x32x16_bf16 v[34:49], v[84:87], v[68:71], v[34:49]
	v_mfma_f32_32x32x16_bf16 v[34:49], v[88:91], v[72:75], v[34:49]
	v_mfma_f32_32x32x16_bf16 v[34:49], v[92:95], v[76:79], v[34:49]
	v_mfma_f32_32x32x16_bf16 v[34:49], v[156:159], v[80:83], v[34:49]
	s_setprio 0
	ds_read_b128 v[84:87], v0 offset:28672
	ds_read_b128 v[88:91], v193 offset:12288
	ds_read_b128 v[92:95], v194 offset:12288
	ds_read_b128 v[156:159], v195 offset:12288
	s_setprio 1
	v_mfma_f32_32x32x16_bf16 v[18:33], v[130:133], v[68:71], v[18:33]
	v_mfma_f32_32x32x16_bf16 v[18:33], v[134:137], v[72:75], v[18:33]
	v_mfma_f32_32x32x16_bf16 v[18:33], v[138:141], v[76:79], v[18:33]
	v_mfma_f32_32x32x16_bf16 v[18:33], v[142:145], v[80:83], v[18:33]
	s_setprio 0
	s_setprio 1
	s_waitcnt lgkmcnt(0)
	v_mfma_f32_32x32x16_bf16 v[2:17], v[84:87], v[68:71], v[2:17]
	v_mfma_f32_32x32x16_bf16 v[2:17], v[88:91], v[72:75], v[2:17]
	v_mfma_f32_32x32x16_bf16 v[2:17], v[92:95], v[76:79], v[2:17]
	v_mfma_f32_32x32x16_bf16 v[2:17], v[156:159], v[80:83], v[2:17]
	s_setprio 0
	s_branch .LBB0_1160
.Lfx_skipdma:
	s_add_i32 s8, s16, 2
	s_cmp_ge_u32 s8, s36
	s_cbranch_scc1 .LBB0_1159
	s_add_i32 s8, s3, s14
	v_lshl_add_u64 v[66:67], s[30:31], 0, v[154:155]
	s_mov_b32 m0, s8
	s_nop 0
	global_load_lds_dwordx4 v[66:67], off
	s_add_i32 m0, s8, 0x400
	s_add_i32 s8, s14, 0
	v_lshl_add_u64 v[66:67], s[30:31], 0, v[152:153]
	s_add_i32 s9, s8, s2
	global_load_lds_dwordx4 v[66:67], off
	s_add_i32 m0, s9, 0x4000
	v_lshl_add_u64 v[66:67], s[30:31], 0, v[150:151]
	global_load_lds_dwordx4 v[66:67], off
	v_lshl_add_u64 v[66:67], s[30:31], 0, v[148:149]
	s_add_i32 m0, s9, 0x4400
	s_add_i32 s8, s8, s12
	global_load_lds_dwordx4 v[66:67], off
	v_lshl_add_u64 v[66:67], s[30:31], 0, v[146:147]
	s_add_i32 m0, s8, 0x8000
	s_nop 0
	global_load_lds_dword v[66:67], off
